# grid barrier: first arriver per XCD issues an async L2 writeback so the XCD leader's release fence is cheaper; on top of v006
# speedup vs baseline: 1.0022x; 1.0022x over previous
; __device__ __forceinline__ unsigned xb_ld(unsigned* p)              { return __hip_atomic_load(p, __ATOMIC_RELAXED, __HIP_MEMORY_SCOPE_AGENT); }
; __device__ __forceinline__ unsigned xb_add(unsigned* p, unsigned v) { return __hip_atomic_fetch_add(p, v, __ATOMIC_RELAXED, __HIP_MEMORY_SCOPE_AGENT); }
; #define XB_SPIN(cond, bar) do { unsigned _sp = 0; while (cond) { __builtin_amdgcn_s_sleep(1); \
;     if ((++_sp & 255u) == 0u) { if (xb_ld(&(bar)[XB_TMO])) break; if (_sp > XB_SPIN_CAP) { atomicAdd(&(bar)[XB_TMO], 1u); break; } } } } while (0)
; __device__ __forceinline__ void xcd_barrier(const XcdBarrier& b) {
;     ...
;         unsigned nloc = b.st[0], nx = b.st[1];
;         if (nloc == 0u) { xcd_barrier_complete(bar, b.x, nloc, nx); b.st[0] = nloc; b.st[1] = nx; }
;         const unsigned old = xb_add(&bar[XB_XSUB(b.x)], 1u);
;         const unsigned gen = old / nloc;
;         if (old + 1u == (gen + 1u) * nloc) {
;             __builtin_amdgcn_fence(__ATOMIC_RELEASE, "agent");
;             asm volatile("s_waitcnt vmcnt(0)" ::: "memory");
;             const unsigned og = xb_add(&bar[XB_TOP], 1u);
;             const unsigned tg = og / nx;
;             if (og + 1u == (tg + 1u) * nx) xb_add(&bar[XB_TOPGEN], 1u);
;             else XB_SPIN(xb_ld(&bar[XB_TOPGEN]) == tg, bar);
;             __builtin_amdgcn_fence(__ATOMIC_ACQUIRE, "agent");
;             xb_add(&bar[XB_XGEN(b.x)], 1u);
;             asm volatile("s_waitcnt vmcnt(0)" ::: "memory");
;         } else {
;             XB_SPIN(xb_ld(&bar[XB_XGEN(b.x)]) == gen, bar);
;             __builtin_amdgcn_fence(__ATOMIC_ACQUIRE, "agent");
;             asm volatile("s_waitcnt vmcnt(0)" ::: "memory");
.LBB0_129:
	s_or_b64 exec, exec, s[18:19]
	v_cvt_f32_u32_e32 v4, v2
	s_waitcnt vmcnt(0)
	v_readfirstlane_b32 s2, v3
	v_sub_u32_e32 v3, 0, v2
	v_rcp_iflag_f32_e32 v4, v4
	v_add_u32_e32 v5, s2, v1
	v_mul_f32_e32 v4, 0x4f7ffffe, v4
	v_cvt_u32_f32_e32 v4, v4
	v_mul_lo_u32 v1, v3, v4
	v_mul_hi_u32 v1, v4, v1
	v_add_u32_e32 v1, v4, v1
	v_mul_hi_u32 v1, v5, v1
	v_mul_lo_u32 v3, v1, v2
	v_sub_u32_e32 v3, v5, v3
	v_add_u32_e32 v4, 1, v1
	v_cmp_ge_u32_e32 vcc, v3, v2
	s_nop 1
	v_cndmask_b32_e32 v1, v1, v4, vcc
	v_sub_u32_e32 v4, v3, v2
	v_cndmask_b32_e32 v3, v3, v4, vcc
	v_add_u32_e32 v4, 1, v1
	v_cmp_ge_u32_e32 vcc, v3, v2
	v_add_u32_e32 v3, 1, v5
	s_nop 0
	v_cndmask_b32_e32 v1, v1, v4, vcc
	v_mul_lo_u32 v4, v2, v1
	v_add_u32_e32 v2, v4, v2
	v_cmp_ne_u32_e32 vcc, v3, v2
	s_and_saveexec_b64 s[2:3], vcc
	s_xor_b64 s[16:17], exec, s[2:3]
	s_cbranch_execz .LBB0_143
	v_cmp_eq_u32_e32 vcc, v5, v4
	s_and_saveexec_b64 s[100:101], vcc
	s_cbranch_execz .Lxbf_1
	buffer_wbl2 sc1
.Lxbf_1:
	s_mov_b64 exec, s[100:101]
	s_waitcnt lgkmcnt(0)
	v_mov_b32_e32 v0, 0x2000
	global_load_dword v0, v0, s[4:5] offset:1024 sc1
	s_add_u32 s20, s4, 0x2400
	s_addc_u32 s21, s5, 0
	s_waitcnt vmcnt(0)
	v_cmp_eq_u32_e32 vcc, v0, v1
	s_and_saveexec_b64 s[18:19], vcc
	s_cbranch_execz .LBB0_142
	s_mov_b32 s2, 1
	s_mov_b64 s[22:23], 0
	v_mov_b32_e32 v0, 0
	s_branch .LBB0_133

; __device__ __forceinline__ unsigned xb_ld(unsigned* p)              { return __hip_atomic_load(p, __ATOMIC_RELAXED, __HIP_MEMORY_SCOPE_AGENT); }
; __device__ __forceinline__ unsigned xb_add(unsigned* p, unsigned v) { return __hip_atomic_fetch_add(p, v, __ATOMIC_RELAXED, __HIP_MEMORY_SCOPE_AGENT); }
; #define XB_SPIN(cond, bar) do { unsigned _sp = 0; while (cond) { __builtin_amdgcn_s_sleep(1); \
;     if ((++_sp & 255u) == 0u) { if (xb_ld(&(bar)[XB_TMO])) break; if (_sp > XB_SPIN_CAP) { atomicAdd(&(bar)[XB_TMO], 1u); break; } } } } while (0)
; __device__ __forceinline__ void xcd_barrier(const XcdBarrier& b) {
;     ...
;         unsigned nloc = b.st[0], nx = b.st[1];
;         if (nloc == 0u) { xcd_barrier_complete(bar, b.x, nloc, nx); b.st[0] = nloc; b.st[1] = nx; }
;         const unsigned old = xb_add(&bar[XB_XSUB(b.x)], 1u);
;         const unsigned gen = old / nloc;
;         if (old + 1u == (gen + 1u) * nloc) {
;             __builtin_amdgcn_fence(__ATOMIC_RELEASE, "agent");
;             asm volatile("s_waitcnt vmcnt(0)" ::: "memory");
;             const unsigned og = xb_add(&bar[XB_TOP], 1u);
;             const unsigned tg = og / nx;
;             if (og + 1u == (tg + 1u) * nx) xb_add(&bar[XB_TOPGEN], 1u);
;             else XB_SPIN(xb_ld(&bar[XB_TOPGEN]) == tg, bar);
;             __builtin_amdgcn_fence(__ATOMIC_ACQUIRE, "agent");
;             xb_add(&bar[XB_XGEN(b.x)], 1u);
;             asm volatile("s_waitcnt vmcnt(0)" ::: "memory");
;         } else {
;             XB_SPIN(xb_ld(&bar[XB_XGEN(b.x)]) == gen, bar);
;             __builtin_amdgcn_fence(__ATOMIC_ACQUIRE, "agent");
;             asm volatile("s_waitcnt vmcnt(0)" ::: "memory");
.LBB0_205:
	s_or_b64 exec, exec, s[8:9]
	v_cvt_f32_u32_e32 v4, v2
	s_waitcnt vmcnt(0)
	v_readfirstlane_b32 s2, v3
	v_sub_u32_e32 v3, 0, v2
	v_rcp_iflag_f32_e32 v4, v4
	v_add_u32_e32 v5, s2, v1
	v_mul_f32_e32 v4, 0x4f7ffffe, v4
	v_cvt_u32_f32_e32 v4, v4
	v_mul_lo_u32 v1, v3, v4
	v_mul_hi_u32 v1, v4, v1
	v_add_u32_e32 v1, v4, v1
	v_mul_hi_u32 v1, v5, v1
	v_mul_lo_u32 v3, v1, v2
	v_sub_u32_e32 v3, v5, v3
	v_add_u32_e32 v4, 1, v1
	v_cmp_ge_u32_e32 vcc, v3, v2
	s_nop 1
	v_cndmask_b32_e32 v1, v1, v4, vcc
	v_sub_u32_e32 v4, v3, v2
	v_cndmask_b32_e32 v3, v3, v4, vcc
	v_add_u32_e32 v4, 1, v1
	v_cmp_ge_u32_e32 vcc, v3, v2
	v_add_u32_e32 v3, 1, v5
	s_nop 0
	v_cndmask_b32_e32 v1, v1, v4, vcc
	v_mul_lo_u32 v4, v2, v1
	v_add_u32_e32 v2, v4, v2
	v_cmp_ne_u32_e32 vcc, v3, v2
	s_and_saveexec_b64 s[2:3], vcc
	s_xor_b64 s[6:7], exec, s[2:3]
	s_cbranch_execz .LBB0_219
	v_cmp_eq_u32_e32 vcc, v5, v4
	s_and_saveexec_b64 s[100:101], vcc
	s_cbranch_execz .Lxbf_2
	buffer_wbl2 sc1
.Lxbf_2:
	s_mov_b64 exec, s[100:101]
	s_waitcnt lgkmcnt(0)
	v_mov_b32_e32 v0, 0x2000
	global_load_dword v0, v0, s[4:5] offset:1024 sc1
	s_add_u32 s16, s4, 0x2400
	s_addc_u32 s17, s5, 0
	s_waitcnt vmcnt(0)
	v_cmp_eq_u32_e32 vcc, v0, v1
	s_and_saveexec_b64 s[8:9], vcc
	s_cbranch_execz .LBB0_218
	s_mov_b32 s2, 1
	s_mov_b64 s[18:19], 0
	v_mov_b32_e32 v0, 0
	s_branch .LBB0_209

; __device__ __forceinline__ unsigned xb_ld(unsigned* p)              { return __hip_atomic_load(p, __ATOMIC_RELAXED, __HIP_MEMORY_SCOPE_AGENT); }
; #define XB_SPIN(cond, bar) do { unsigned _sp = 0; while (cond) { __builtin_amdgcn_s_sleep(1); \
;     if ((++_sp & 255u) == 0u) { if (xb_ld(&(bar)[XB_TMO])) break; if (_sp > XB_SPIN_CAP) { atomicAdd(&(bar)[XB_TMO], 1u); break; } } } } while (0)
; __device__ __forceinline__ void xcd_barrier(const XcdBarrier& b) {
;     ...
;             XB_SPIN(xb_ld(&bar[XB_XGEN(b.x)]) == gen, bar);
;             __builtin_amdgcn_fence(__ATOMIC_ACQUIRE, "agent");
;             asm volatile("s_waitcnt vmcnt(0)" ::: "memory");
.Lxbf_3:
	s_mov_b64 exec, s[100:101]
	s_waitcnt lgkmcnt(0)
	v_mov_b32_e32 v0, 0x2000
	global_load_dword v0, v0, s[4:5] offset:1024 sc1
	s_add_u32 s10, s4, 0x2400
	s_addc_u32 s11, s5, 0
	s_waitcnt vmcnt(0)
	v_cmp_eq_u32_e32 vcc, v0, v1
	s_and_saveexec_b64 s[8:9], vcc
	s_cbranch_execz .LBB0_334
	s_mov_b32 s2, 1
	s_mov_b64 s[16:17], 0
	v_mov_b32_e32 v0, 0
	s_branch .LBB0_325

; __device__ __forceinline__ unsigned xb_ld(unsigned* p)              { return __hip_atomic_load(p, __ATOMIC_RELAXED, __HIP_MEMORY_SCOPE_AGENT); }
; __device__ __forceinline__ unsigned xb_add(unsigned* p, unsigned v) { return __hip_atomic_fetch_add(p, v, __ATOMIC_RELAXED, __HIP_MEMORY_SCOPE_AGENT); }
; #define XB_SPIN(cond, bar) do { unsigned _sp = 0; while (cond) { __builtin_amdgcn_s_sleep(1); \
;     if ((++_sp & 255u) == 0u) { if (xb_ld(&(bar)[XB_TMO])) break; if (_sp > XB_SPIN_CAP) { atomicAdd(&(bar)[XB_TMO], 1u); break; } } } } while (0)
; __device__ __forceinline__ void xcd_barrier(const XcdBarrier& b) {
;     ...
;         unsigned nloc = b.st[0], nx = b.st[1];
;         if (nloc == 0u) { xcd_barrier_complete(bar, b.x, nloc, nx); b.st[0] = nloc; b.st[1] = nx; }
;         const unsigned old = xb_add(&bar[XB_XSUB(b.x)], 1u);
;         const unsigned gen = old / nloc;
;         if (old + 1u == (gen + 1u) * nloc) {
;             __builtin_amdgcn_fence(__ATOMIC_RELEASE, "agent");
;             asm volatile("s_waitcnt vmcnt(0)" ::: "memory");
;             const unsigned og = xb_add(&bar[XB_TOP], 1u);
;             const unsigned tg = og / nx;
;             if (og + 1u == (tg + 1u) * nx) xb_add(&bar[XB_TOPGEN], 1u);
;             else XB_SPIN(xb_ld(&bar[XB_TOPGEN]) == tg, bar);
;             __builtin_amdgcn_fence(__ATOMIC_ACQUIRE, "agent");
;             xb_add(&bar[XB_XGEN(b.x)], 1u);
;             asm volatile("s_waitcnt vmcnt(0)" ::: "memory");
;         } else {
;             XB_SPIN(xb_ld(&bar[XB_XGEN(b.x)]) == gen, bar);
;             __builtin_amdgcn_fence(__ATOMIC_ACQUIRE, "agent");
;             asm volatile("s_waitcnt vmcnt(0)" ::: "memory");
.LBB0_383:
	s_or_b64 exec, exec, s[8:9]
	v_cvt_f32_u32_e32 v4, v2
	s_waitcnt vmcnt(0)
	v_readfirstlane_b32 s6, v3
	v_sub_u32_e32 v3, 0, v2
	v_rcp_iflag_f32_e32 v4, v4
	v_add_u32_e32 v5, s6, v1
	v_mul_f32_e32 v4, 0x4f7ffffe, v4
	v_cvt_u32_f32_e32 v4, v4
	v_mul_lo_u32 v1, v3, v4
	v_mul_hi_u32 v1, v4, v1
	v_add_u32_e32 v1, v4, v1
	v_mul_hi_u32 v1, v5, v1
	v_mul_lo_u32 v3, v1, v2
	v_sub_u32_e32 v3, v5, v3
	v_add_u32_e32 v4, 1, v1
	v_cmp_ge_u32_e32 vcc, v3, v2
	s_nop 1
	v_cndmask_b32_e32 v1, v1, v4, vcc
	v_sub_u32_e32 v4, v3, v2
	v_cndmask_b32_e32 v3, v3, v4, vcc
	v_add_u32_e32 v4, 1, v1
	v_cmp_ge_u32_e32 vcc, v3, v2
	v_add_u32_e32 v3, 1, v5
	s_nop 0
	v_cndmask_b32_e32 v1, v1, v4, vcc
	v_mul_lo_u32 v4, v2, v1
	v_add_u32_e32 v2, v4, v2
	v_cmp_ne_u32_e32 vcc, v3, v2
	s_and_saveexec_b64 s[6:7], vcc
	s_xor_b64 s[6:7], exec, s[6:7]
	s_cbranch_execz .LBB0_397
	v_cmp_eq_u32_e32 vcc, v5, v4
	s_and_saveexec_b64 s[100:101], vcc
	s_cbranch_execz .Lxbf_4
	buffer_wbl2 sc1
.Lxbf_4:
	s_mov_b64 exec, s[100:101]
	s_waitcnt lgkmcnt(0)
	v_mov_b32_e32 v0, 0x2000
	global_load_dword v0, v0, s[4:5] offset:1024 sc1
	s_add_u32 s10, s4, 0x2400
	s_addc_u32 s11, s5, 0
	s_waitcnt vmcnt(0)
	v_cmp_eq_u32_e32 vcc, v0, v1
	s_and_saveexec_b64 s[8:9], vcc
	s_cbranch_execz .LBB0_396
	s_mov_b32 s33, 1
	s_mov_b64 s[16:17], 0
	v_mov_b32_e32 v0, 0
	s_branch .LBB0_387

; __device__ __forceinline__ unsigned xb_ld(unsigned* p)              { return __hip_atomic_load(p, __ATOMIC_RELAXED, __HIP_MEMORY_SCOPE_AGENT); }
; #define XB_SPIN(cond, bar) do { unsigned _sp = 0; while (cond) { __builtin_amdgcn_s_sleep(1); \
;     if ((++_sp & 255u) == 0u) { if (xb_ld(&(bar)[XB_TMO])) break; if (_sp > XB_SPIN_CAP) { atomicAdd(&(bar)[XB_TMO], 1u); break; } } } } while (0)
; __device__ __forceinline__ void xcd_barrier(const XcdBarrier& b) {
;     ...
;             XB_SPIN(xb_ld(&bar[XB_XGEN(b.x)]) == gen, bar);
;             __builtin_amdgcn_fence(__ATOMIC_ACQUIRE, "agent");
;             asm volatile("s_waitcnt vmcnt(0)" ::: "memory");
.Lxbf_5:
	s_mov_b64 exec, s[100:101]
	s_waitcnt lgkmcnt(0)
	v_mov_b32_e32 v0, 0x2000
	global_load_dword v0, v0, s[4:5] offset:1024 sc1
	s_add_u32 s10, s4, 0x2400
	s_addc_u32 s11, s5, 0
	s_waitcnt vmcnt(0)
	v_cmp_eq_u32_e32 vcc, v0, v1
	s_and_saveexec_b64 s[8:9], vcc
	s_cbranch_execz .LBB0_556
	s_mov_b32 s22, 1
	s_mov_b64 s[12:13], 0
	v_mov_b32_e32 v0, 0
	s_branch .LBB0_547

; __device__ __forceinline__ unsigned xb_ld(unsigned* p)              { return __hip_atomic_load(p, __ATOMIC_RELAXED, __HIP_MEMORY_SCOPE_AGENT); }
; #define XB_SPIN(cond, bar) do { unsigned _sp = 0; while (cond) { __builtin_amdgcn_s_sleep(1); \
;     if ((++_sp & 255u) == 0u) { if (xb_ld(&(bar)[XB_TMO])) break; if (_sp > XB_SPIN_CAP) { atomicAdd(&(bar)[XB_TMO], 1u); break; } } } } while (0)
; __device__ __forceinline__ void xcd_barrier(const XcdBarrier& b) {
;     ...
;             XB_SPIN(xb_ld(&bar[XB_XGEN(b.x)]) == gen, bar);
;             __builtin_amdgcn_fence(__ATOMIC_ACQUIRE, "agent");
;             asm volatile("s_waitcnt vmcnt(0)" ::: "memory");
.Lxbf_6:
	s_mov_b64 exec, s[100:101]
	s_waitcnt lgkmcnt(0)
	v_mov_b32_e32 v0, 0x2000
	global_load_dword v0, v0, s[4:5] offset:1024 sc1
	s_add_u32 s10, s4, 0x2400
	s_addc_u32 s11, s5, 0
	s_waitcnt vmcnt(0)
	v_cmp_eq_u32_e32 vcc, v0, v1
	s_and_saveexec_b64 s[8:9], vcc
	s_cbranch_execz .LBB0_715
	s_mov_b32 s2, 1
	s_mov_b64 s[12:13], 0
	v_mov_b32_e32 v0, 0
	s_branch .LBB0_706

; __device__ __forceinline__ unsigned xb_ld(unsigned* p)              { return __hip_atomic_load(p, __ATOMIC_RELAXED, __HIP_MEMORY_SCOPE_AGENT); }
; __device__ __forceinline__ unsigned xb_add(unsigned* p, unsigned v) { return __hip_atomic_fetch_add(p, v, __ATOMIC_RELAXED, __HIP_MEMORY_SCOPE_AGENT); }
; #define XB_SPIN(cond, bar) do { unsigned _sp = 0; while (cond) { __builtin_amdgcn_s_sleep(1); \
;     if ((++_sp & 255u) == 0u) { if (xb_ld(&(bar)[XB_TMO])) break; if (_sp > XB_SPIN_CAP) { atomicAdd(&(bar)[XB_TMO], 1u); break; } } } } while (0)
; __device__ __forceinline__ void xcd_barrier(const XcdBarrier& b) {
;     ...
;         unsigned nloc = b.st[0], nx = b.st[1];
;         if (nloc == 0u) { xcd_barrier_complete(bar, b.x, nloc, nx); b.st[0] = nloc; b.st[1] = nx; }
;         const unsigned old = xb_add(&bar[XB_XSUB(b.x)], 1u);
;         const unsigned gen = old / nloc;
;         if (old + 1u == (gen + 1u) * nloc) {
;             __builtin_amdgcn_fence(__ATOMIC_RELEASE, "agent");
;             asm volatile("s_waitcnt vmcnt(0)" ::: "memory");
;             const unsigned og = xb_add(&bar[XB_TOP], 1u);
;             const unsigned tg = og / nx;
;             if (og + 1u == (tg + 1u) * nx) xb_add(&bar[XB_TOPGEN], 1u);
;             else XB_SPIN(xb_ld(&bar[XB_TOPGEN]) == tg, bar);
;             __builtin_amdgcn_fence(__ATOMIC_ACQUIRE, "agent");
;             xb_add(&bar[XB_XGEN(b.x)], 1u);
;             asm volatile("s_waitcnt vmcnt(0)" ::: "memory");
;         } else {
;             XB_SPIN(xb_ld(&bar[XB_XGEN(b.x)]) == gen, bar);
;             __builtin_amdgcn_fence(__ATOMIC_ACQUIRE, "agent");
;             asm volatile("s_waitcnt vmcnt(0)" ::: "memory");
.LBB0_917:
	s_or_b64 exec, exec, s[10:11]
	v_cvt_f32_u32_e32 v4, v2
	s_waitcnt vmcnt(0)
	v_readfirstlane_b32 s2, v3
	v_sub_u32_e32 v3, 0, v2
	v_rcp_iflag_f32_e32 v4, v4
	v_add_u32_e32 v5, s2, v1
	v_mul_f32_e32 v4, 0x4f7ffffe, v4
	v_cvt_u32_f32_e32 v4, v4
	v_mul_lo_u32 v1, v3, v4
	v_mul_hi_u32 v1, v4, v1
	v_add_u32_e32 v1, v4, v1
	v_mul_hi_u32 v1, v5, v1
	v_mul_lo_u32 v3, v1, v2
	v_sub_u32_e32 v3, v5, v3
	v_add_u32_e32 v4, 1, v1
	v_cmp_ge_u32_e32 vcc, v3, v2
	s_nop 1
	v_cndmask_b32_e32 v1, v1, v4, vcc
	v_sub_u32_e32 v4, v3, v2
	v_cndmask_b32_e32 v3, v3, v4, vcc
	v_add_u32_e32 v4, 1, v1
	v_cmp_ge_u32_e32 vcc, v3, v2
	v_add_u32_e32 v3, 1, v5
	s_nop 0
	v_cndmask_b32_e32 v1, v1, v4, vcc
	v_mul_lo_u32 v4, v2, v1
	v_add_u32_e32 v2, v4, v2
	v_cmp_ne_u32_e32 vcc, v3, v2
	s_and_saveexec_b64 s[2:3], vcc
	s_xor_b64 s[8:9], exec, s[2:3]
	s_cbranch_execz .LBB0_931
	v_cmp_eq_u32_e32 vcc, v5, v4
	s_and_saveexec_b64 s[100:101], vcc
	s_cbranch_execz .Lxbf_8
	buffer_wbl2 sc1
.Lxbf_8:
	s_mov_b64 exec, s[100:101]
	s_waitcnt lgkmcnt(0)
	v_mov_b32_e32 v0, 0x2000
	global_load_dword v0, v0, s[6:7] offset:1024 sc1
	s_add_u32 s12, s6, 0x2400
	s_addc_u32 s13, s7, 0
	s_waitcnt vmcnt(0)
	v_cmp_eq_u32_e32 vcc, v0, v1
	s_and_saveexec_b64 s[10:11], vcc
	s_cbranch_execz .LBB0_930
	s_mov_b32 s2, 1
	s_mov_b64 s[14:15], 0
	v_mov_b32_e32 v0, 0
	s_branch .LBB0_921
